# seam 3 replaced by a split 32-workgroup barrier (arrive after LRU pass 1, wait before the LRU carry); cumsum ahead of seam 2
# speedup vs baseline: 1.0098x; 1.0098x over previous
.LBB0_303:
	s_barrier
	s_getreg_b32 s2, hwreg(HW_REG_XCC_ID, 0, 4)
	s_waitcnt vmcnt(0)
	s_barrier
	s_mov_b64 s[0:1], exec
	v_readlane_b32 s4, v255, 2
	v_readlane_b32 s5, v255, 3
	s_and_b64 s[4:5], s[0:1], s[4:5]
	s_mov_b64 exec, s[4:5]
	s_cbranch_execz .Ls3_arrived
	buffer_wbl2 sc1
	s_waitcnt vmcnt(0)
	v_readlane_b32 s2, v255, 0
	s_add_u32 s4, s92, 0x3800
	s_addc_u32 s5, s93, 0
	s_and_b32 s2, s2, 7
	s_lshl_b32 s2, s2, 7
	v_mov_b32_e32 v0, s2
	v_mov_b32_e32 v1, 1
	global_atomic_add v0, v1, s[4:5]
	s_waitcnt vmcnt(0)

.LBB0_478:
	s_mov_b64 s[0:1], exec
	v_readlane_b32 s4, v255, 2
	v_readlane_b32 s5, v255, 3
	s_and_b64 s[4:5], s[0:1], s[4:5]
	s_mov_b64 exec, s[4:5]
	s_cbranch_execz .Ls3_released
	v_readlane_b32 s2, v255, 0
	s_add_u32 s4, s92, 0x3800
	s_addc_u32 s5, s93, 0
	s_and_b32 s2, s2, 7
	s_lshl_b32 s2, s2, 7
	v_mov_b32_e32 v0, s2
.Ls3_poll:
	global_load_dword v1, v0, s[4:5] sc1
	s_waitcnt vmcnt(0)
	v_readfirstlane_b32 s2, v1
	s_nop 0
	s_cmp_lt_u32 s2, 32
	s_cbranch_scc0 .Ls3_acquire
	s_sleep 1
	s_branch .Ls3_poll
.Ls3_acquire:
	buffer_inv sc1
	s_waitcnt vmcnt(0)
.Ls3_released:
	s_or_b64 exec, exec, s[0:1]
	s_barrier
	v_mov_b32_e32 v71, v204
	s_movk_i32 s0, 0x7f
	v_ashrrev_i32_e32 v0, 2, v71
	v_and_b32_e32 v0, 0xffffffe0, v0
	v_cmp_lt_u32_e32 vcc, s0, v71
	v_readlane_b32 s0, v255, 4
	v_add_u32_e32 v69, s87, v0
	s_and_b32 s2, s0, 0xe00
	v_and_b32_e32 v70, 0x7f, v71
	v_subrev_u32_e32 v0, 32, v69
	s_add_u32 s0, s80, s2
	v_cndmask_b32_e32 v2, 0, v0, vcc
	s_addc_u32 s1, s81, 0
	v_lshlrev_b32_e32 v0, 2, v70
	v_mov_b32_e32 v1, 0
	v_lshl_add_u64 v[8:9], s[0:1], 0, v[0:1]
	s_add_u32 s0, s82, s2
	s_addc_u32 s1, s83, 0
	v_lshl_add_u64 v[14:15], s[0:1], 0, v[0:1]
	v_mov_b32_e32 v0, 1.0
	v_ashrrev_i32_e32 v3, 31, v2
	v_mov_b32_e32 v72, 1.0
	v_mov_b32_e32 v73, 0
	v_cmp_lt_i32_e64 s[2:3], v2, v69
	s_mov_b64 s[0:1], exec
	s_nop 0
	v_writelane_b32 v255, s2, 4
	s_nop 1
	v_writelane_b32 v255, s3, 5
	s_and_b64 s[2:3], s[0:1], s[2:3]
	s_mov_b64 exec, s[2:3]
	s_cbranch_execz .LBB0_480
	v_lshlrev_b64 v[4:5], 12, v[2:3]
	v_lshl_add_u64 v[6:7], v[8:9], 0, v[4:5]
	v_lshl_add_u64 v[4:5], v[14:15], 0, v[4:5]
	global_load_dword v72, v[6:7], off
	global_load_dword v73, v[4:5], off
